# diff_attn main loop: Q/K fragment LDS reads interleaved (Q0,K0,Q1,K1..) with counted lgkmcnt so S MFMAs start after 2 reads instead of 9 (stacked on v11)
# speedup vs baseline: 1.0021x; 1.0021x over previous
; #define LAS __attribute__((address_space(3)))
; #define MFMA32(a, b, c) __builtin_amdgcn_mfma_f32_32x32x16_bf16((a), (b), (c), 0, 0, 0)
; DI f32x16 zero16() { f32x16 z; for (int i = 0; i < 16; ++i) z[i] = 0.f; return z; }
; DI void diff_attn_phase(int wv, LAS unsigned char* lds, const bf16_t* qk, const bf16_t* vt, bf16_t* ob, const float* lq1, const float* lk1, const float* lq2, const float* lk2,
;                         const float* subg, int layer_idx) {
;     ...
;         for (int t = 0; t < tmain; ++t) {
;             const int key0 = t * 64;
;             const bool more = true;
;             if (more) {
; #pragma unroll
;                 for (int i = 0; i < 2; ++i) gk[i] = *(const u32x4*)(kg + (size_t)(key0 + 64 + i * 32) * 2048); }
;             LAS unsigned char* buf = lds + (t & 1) * DA_BUF;
;             {
;                 f32x16 S0 = zero16(), S1 = zero16();
;                 {
;                     bf16x8 kf[2][4];
; #pragma unroll
;                     for (int sub = 0; sub < 2; ++sub)
; #pragma unroll
;                         for (int ks = 0; ks < 4; ++ks) kf[sub][ks] = *(const LAS bf16x8*)(buf + koff + sub * 32 * DA_KP + ks * 32);
; #pragma unroll
;                     for (int ks = 0; ks < 4; ++ks) { const bf16x8 qfr = *(const LAS bf16x8*)(qlds + ks * 1024); S0 = MFMA32(kf[0][ks], qfr, S0); S1 = MFMA32(kf[1][ks], qfr, S1); }
;                 }
;                 __builtin_amdgcn_sched_barrier(0);
; #pragma unroll
;                 for (int i = 0; i < 2; ++i) gv[i] = *(const u32x4*)(vg + (size_t)i * 64 * M_TOK + key0 + 64);
;                 bf16x8 vf[4][2];
; #pragma unroll
;                 for (int d = 0; d < 4; ++d)
; #pragma unroll
;                     for (int s2 = 0; s2 < 2; ++s2) vf[d][s2] = *(const LAS bf16x8*)(buf + voff + d * 32 * DA_VP + (16 * s2) * 2);
;                 const float base = slope2 * (float)(key0 + 8 * hh - qpos), b32 = 32.f * slope2;
; #pragma unroll
;                 for (int i = 0; i < 16; ++i) { S0[i] = S0[i] * c1 + cb[i]; S1[i] = S1[i] * c1 + cb[i]; }
;                 float mx = -INFINITY, mx1 = -INFINITY;
; #pragma unroll
;                 for (int i = 0; i < 16; ++i) { mx = fmaxf(mx, S0[i]); mx1 = fmaxf(mx1, S1[i]); }
;                 mx = fmaxf(mx, mx1 + b32) + base;
;                 mx = fmaxf(mx, __shfl_xor(mx, 32));
.LBB0_424:
	s_add_i32 s14, s16, 64
	s_ashr_i32 s15, s14, 31
	s_lshl_b64 s[26:27], s[14:15], 12
	v_lshl_add_u64 v[66:67], v[114:115], 0, s[26:27]
	s_add_i32 s26, s16, 0x60
	s_ashr_i32 s27, s26, 31
	s_lshl_b64 s[26:27], s[26:27], 12
	global_load_dwordx4 v[98:101], v[66:67], off offset:2048
	v_lshl_add_u64 v[66:67], v[114:115], 0, s[26:27]
	global_load_dwordx4 v[102:105], v[66:67], off offset:2048
	s_bitcmp1_b32 s25, 0
	s_cselect_b32 s2, 0x8c00, 0
	s_add_i32 s2, s2, 0
	v_add_u32_e32 v70, s2, v153
	ds_read_b128 v[126:129], v217
	ds_read_b128 v[66:69], v70
	ds_read_b128 v[130:133], v217 offset:1024
	ds_read_b128 v[82:85], v70 offset:32
	ds_read_b128 v[134:137], v217 offset:2048
	ds_read_b128 v[86:89], v70 offset:64
	ds_read_b128 v[138:141], v217 offset:3072
	ds_read_b128 v[90:93], v70 offset:96
	ds_read_b128 v[94:97], v70 offset:8704
	ds_read_b128 v[106:109], v70 offset:8736
	ds_read_b128 v[110:113], v70 offset:8768
	ds_read_b128 v[122:125], v70 offset:8800
	v_mov_b32_e32 v121, v159
	v_mov_b32_e32 v0, v218
	s_waitcnt lgkmcnt(10)
	v_mfma_f32_32x32x16_bf16 v[66:81], v[66:69], v[126:129], 0
	s_ashr_i32 s17, s16, 31
	s_mov_b32 s3, 0x400000
	v_add_u32_e32 v118, s16, v120
	v_add_u32_e32 v191, s2, v211
	s_waitcnt lgkmcnt(8)
	v_mfma_f32_32x32x16_bf16 v[66:81], v[82:85], v[130:133], v[66:81]
	s_waitcnt lgkmcnt(6)
	v_mfma_f32_32x32x16_bf16 v[66:81], v[86:89], v[134:137], v[66:81]
	s_waitcnt lgkmcnt(4)
	v_mfma_f32_32x32x16_bf16 v[66:81], v[90:93], v[138:141], v[66:81]
	s_waitcnt lgkmcnt(3)
	v_mfma_f32_32x32x16_bf16 v[82:97], v[94:97], v[126:129], 0
	s_nop 10
	v_fmamk_f32 v127, v66, 0x3e38aa3b, v192
	v_max_f32_e32 v66, 0xff800000, v127
	v_fmamk_f32 v129, v69, 0x3e38aa3b, v189
	v_fmamk_f32 v159, v74, 0x3e38aa3b, v182
	v_fmamk_f32 v193, v75, 0x3e38aa3b, v183
	v_fmamk_f32 v196, v76, 0x3e38aa3b, v180
	v_cvt_f32_i32_e32 v126, v118
	s_waitcnt lgkmcnt(2)
	v_mfma_f32_32x32x16_bf16 v[82:97], v[106:109], v[130:133], v[82:97]
	v_lshl_add_u64 v[106:107], s[16:17], 1, v[116:117]
	v_add_co_u32_e32 v108, vcc, s3, v106
	v_fmamk_f32 v131, v70, 0x3e38aa3b, v186
	s_nop 0
	v_addc_co_u32_e32 v109, vcc, 0, v107, vcc
	v_fmamk_f32 v133, v71, 0x3e38aa3b, v187
	s_waitcnt lgkmcnt(1)
	v_mfma_f32_32x32x16_bf16 v[82:97], v[110:113], v[134:137], v[82:97]
	global_load_dwordx4 v[110:113], v[106:107], off offset:128
	s_nop 0
	global_load_dwordx4 v[106:109], v[108:109], off offset:128
	v_fmamk_f32 v135, v72, 0x3e38aa3b, v184
	v_fmamk_f32 v137, v73, 0x3e38aa3b, v185
	v_fmamk_f32 v199, v77, 0x3e38aa3b, v181
	v_fmamk_f32 v200, v78, 0x3e38aa3b, v178
	v_fmamk_f32 v204, v79, 0x3e38aa3b, v179
	v_fmamk_f32 v207, v80, 0x3e38aa3b, v176
	s_waitcnt lgkmcnt(0)
	v_mfma_f32_32x32x16_bf16 v[82:97], v[122:125], v[138:141], v[82:97]
	v_fmamk_f32 v123, v67, 0x3e38aa3b, v160
	v_fmamk_f32 v125, v68, 0x3e38aa3b, v188
	v_max3_f32 v66, v66, v123, v125
	v_max3_f32 v66, v66, v129, v131
	v_max3_f32 v66, v66, v133, v135
	v_max3_f32 v66, v66, v137, v159
	v_max3_f32 v66, v66, v193, v196
	s_nop 4
	v_fmamk_f32 v122, v82, 0x3e38aa3b, v192
	v_fmamk_f32 v124, v83, 0x3e38aa3b, v160
	v_fmamk_f32 v128, v84, 0x3e38aa3b, v188
	v_fmamk_f32 v130, v85, 0x3e38aa3b, v189
	v_max3_f32 v67, v122, s54, v124
	v_fmamk_f32 v132, v86, 0x3e38aa3b, v186
	v_fmamk_f32 v134, v87, 0x3e38aa3b, v187
	v_max3_f32 v67, v67, v128, v130
	v_fmamk_f32 v136, v88, 0x3e38aa3b, v184
	v_fmamk_f32 v143, v89, 0x3e38aa3b, v185
	v_max3_f32 v67, v67, v132, v134
	v_fmamk_f32 v169, v90, 0x3e38aa3b, v182
	v_fmamk_f32 v195, v91, 0x3e38aa3b, v183
	v_max3_f32 v67, v67, v136, v143
	v_fmamk_f32 v198, v92, 0x3e38aa3b, v180
	v_fmamk_f32 v202, v93, 0x3e38aa3b, v181
	v_max3_f32 v67, v67, v169, v195
	v_fmamk_f32 v203, v94, 0x3e38aa3b, v178
	v_fmamk_f32 v206, v95, 0x3e38aa3b, v179
	v_max3_f32 v67, v67, v198, v202
	v_fmamk_f32 v219, v96, 0x3e38aa3b, v176
	v_fmamk_f32 v222, v97, 0x3e38aa3b, v177
	v_max3_f32 v67, v67, v203, v206
	v_max3_f32 v66, v66, v199, v200
	v_max3_f32 v67, v67, v219, v222
	v_fmamk_f32 v220, v81, 0x3e38aa3b, v177
	v_max3_f32 v66, v66, v204, v207
	v_add_f32_e32 v67, v157, v67
	v_max3_f32 v66, v66, v220, v67
	v_fmac_f32_e32 v66, v160, v126
	v_mov_b32_e32 v67, v66
	s_nop 1
	v_permlane32_swap_b32_e32 v66, v67
	ds_read_b128 v[94:97], v191 offset:17408
	ds_read_b128 v[90:93], v191 offset:17440
	ds_read_b128 v[86:89], v191 offset:22016
	ds_read_b128 v[82:85], v191 offset:22048
	s_waitcnt lgkmcnt(4)
; DI float fexp2(float x) { return __builtin_amdgcn_exp2f(x); }
; DI void diff_attn_phase(int wv, LAS unsigned char* lds, const bf16_t* qk, const bf16_t* vt, bf16_t* ob, const float* lq1, const float* lk1, const float* lq2, const float* lk2,
;                         const float* subg, int layer_idx) {
;     ...
;                     const float mn = fmaxf(m, mx), alpha = fexp2(m - mn); m = mn; l *= alpha;
; #pragma unroll
;                     for (int d = 0; d < 4; ++d) O[d] = O[d] * alpha;
;                 }
;                 const float off = base - m, off1 = off + b32;
;                 float ps = 0.f;
; #pragma unroll
;                 for (int i = 0; i < 16; ++i) { S0[i] = fexp2(S0[i] + off); S1[i] = fexp2(S1[i] + off1); ps += S0[i] + S1[i]; }
;                 l += ps;
;                 const bf16x8 p0 = pack8(S0, 0), p1 = pack8(S0, 1), p2 = pack8(S1, 0), p3 = pack8(S1, 1);
	v_max3_f32 v218, v0, v66, v67
	v_sub_f32_e32 v0, v0, v218
	v_fma_f32 v126, v160, v126, -v218
	v_exp_f32_e32 v118, v0
	v_add_f32_e32 v223, v157, v126
	v_add_f32_e32 v0, v127, v126
	v_exp_f32_e32 v127, v0
	v_add_f32_e32 v0, v122, v223
	v_add_f32_e32 v122, v125, v126
	v_exp_f32_e32 v224, v0
	v_add_f32_e32 v0, v123, v126
	v_exp_f32_e32 v123, v122
	v_add_f32_e32 v122, v128, v223
	v_exp_f32_e32 v225, v122
	v_add_f32_e32 v122, v129, v126
	v_exp_f32_e32 v140, v122
	v_add_f32_e32 v122, v130, v223
	v_exp_f32_e32 v142, v122
	v_add_f32_e32 v122, v133, v126
	v_exp_f32_e32 v144, v122
	v_add_f32_e32 v122, v134, v223
	v_exp_f32_e32 v168, v122
	v_add_f32_e32 v122, v137, v126
	v_exp_f32_e32 v170, v122
	v_add_f32_e32 v122, v143, v223
	v_add_f32_e32 v129, v169, v223
	v_exp_f32_e32 v194, v122
	v_add_f32_e32 v122, v193, v126
	v_exp_f32_e32 v134, v129
	v_add_f32_e32 v129, v196, v126
	v_exp_f32_e32 v196, v122
	v_add_f32_e32 v122, v195, v223
	v_add_f32_e32 v125, v132, v223
	v_add_f32_e32 v130, v198, v223
	v_exp_f32_e32 v198, v122
	v_add_f32_e32 v122, v199, v126
	v_exp_f32_e32 v132, v125
	v_add_f32_e32 v125, v135, v126
	v_exp_f32_e32 v135, v130
	v_add_f32_e32 v130, v200, v126
	v_exp_f32_e32 v200, v122
	v_add_f32_e32 v122, v202, v223
	v_exp_f32_e32 v202, v122
	v_add_f32_e32 v122, v204, v126
	ds_read_b128 v[78:81], v191 offset:26624
	ds_read_b128 v[74:77], v191 offset:26656
	ds_read_b128 v[70:73], v191 offset:31232
	ds_read_b128 v[66:69], v191 offset:31264
	v_exp_f32_e32 v204, v122
	v_add_f32_e32 v122, v206, v223
	v_exp_f32_e32 v138, v0
	v_add_f32_e32 v0, v124, v223
	v_add_f32_e32 v124, v131, v126
	v_add_f32_e32 v128, v136, v223
	v_add_f32_e32 v131, v203, v223
	v_exp_f32_e32 v206, v122
	v_add_f32_e32 v122, v220, v126
	v_exp_f32_e32 v133, v128
	v_add_f32_e32 v128, v159, v126
	v_exp_f32_e32 v136, v131
	v_add_f32_e32 v131, v207, v126
	v_add_f32_e32 v137, v219, v223
	v_exp_f32_e32 v220, v122
	v_add_f32_e32 v122, v222, v223
	v_exp_f32_e32 v0, v0
	v_exp_f32_e32 v124, v124
	v_exp_f32_e32 v125, v125
	v_exp_f32_e32 v128, v128
	v_exp_f32_e32 v129, v129
	v_exp_f32_e32 v130, v130
	v_exp_f32_e32 v131, v131
	v_exp_f32_e32 v137, v137
	v_exp_f32_e32 v222, v122
	v_pk_mul_f32 v[64:65], v[64:65], v[118:119] op_sel_hi:[1,0]
	v_pk_mul_f32 v[62:63], v[62:63], v[118:119] op_sel_hi:[1,0]
	v_pk_mul_f32 v[60:61], v[60:61], v[118:119] op_sel_hi:[1,0]
	v_pk_mul_f32 v[58:59], v[58:59], v[118:119] op_sel_hi:[1,0]
	v_pk_mul_f32 v[56:57], v[56:57], v[118:119] op_sel_hi:[1,0]
	v_pk_mul_f32 v[54:55], v[54:55], v[118:119] op_sel_hi:[1,0]
	v_pk_mul_f32 v[52:53], v[52:53], v[118:119] op_sel_hi:[1,0]
	v_pk_mul_f32 v[50:51], v[50:51], v[118:119] op_sel_hi:[1,0]
	v_pk_mul_f32 v[48:49], v[48:49], v[118:119] op_sel_hi:[1,0]
	v_pk_mul_f32 v[46:47], v[46:47], v[118:119] op_sel_hi:[1,0]
	v_pk_mul_f32 v[44:45], v[44:45], v[118:119] op_sel_hi:[1,0]
	v_pk_mul_f32 v[42:43], v[42:43], v[118:119] op_sel_hi:[1,0]
	v_pk_mul_f32 v[40:41], v[40:41], v[118:119] op_sel_hi:[1,0]
	v_pk_mul_f32 v[38:39], v[38:39], v[118:119] op_sel_hi:[1,0]
	v_pk_mul_f32 v[36:37], v[36:37], v[118:119] op_sel_hi:[1,0]
	v_pk_mul_f32 v[34:35], v[34:35], v[118:119] op_sel_hi:[1,0]
	v_pk_mul_f32 v[32:33], v[32:33], v[118:119] op_sel_hi:[1,0]
	v_pk_mul_f32 v[30:31], v[30:31], v[118:119] op_sel_hi:[1,0]
	v_pk_mul_f32 v[28:29], v[28:29], v[118:119] op_sel_hi:[1,0]
	v_pk_mul_f32 v[26:27], v[26:27], v[118:119] op_sel_hi:[1,0]
	v_pk_mul_f32 v[24:25], v[24:25], v[118:119] op_sel_hi:[1,0]
	v_pk_mul_f32 v[22:23], v[22:23], v[118:119] op_sel_hi:[1,0]
	v_pk_mul_f32 v[20:21], v[20:21], v[118:119] op_sel_hi:[1,0]
	v_pk_mul_f32 v[18:19], v[18:19], v[118:119] op_sel_hi:[1,0]
	v_pk_mul_f32 v[16:17], v[16:17], v[118:119] op_sel_hi:[1,0]
	v_pk_mul_f32 v[14:15], v[14:15], v[118:119] op_sel_hi:[1,0]
	v_pk_mul_f32 v[12:13], v[12:13], v[118:119] op_sel_hi:[1,0]
	v_pk_mul_f32 v[10:11], v[10:11], v[118:119] op_sel_hi:[1,0]
	v_pk_mul_f32 v[8:9], v[8:9], v[118:119] op_sel_hi:[1,0]
	v_pk_mul_f32 v[6:7], v[6:7], v[118:119] op_sel_hi:[1,0]
	v_pk_mul_f32 v[4:5], v[4:5], v[118:119] op_sel_hi:[1,0]
	v_pk_mul_f32 v[2:3], v[2:3], v[118:119] op_sel_hi:[1,0]
	v_add_f32_e32 v139, v127, v224
	v_add_f32_e32 v141, v123, v225
	v_add_f32_e32 v145, v124, v132
	v_add_f32_e32 v171, v125, v133
	v_add_f32_e32 v197, v128, v134
	v_add_f32_e32 v201, v129, v135
	v_add_f32_e32 v205, v130, v136
	v_add_f32_e32 v221, v131, v137
	v_cvt_pk_bf16_f32 v122, v127, v138
	v_cvt_pk_bf16_f32 v123, v123, v140
	v_cvt_pk_bf16_f32 v124, v124, v144
	v_cvt_pk_bf16_f32 v125, v125, v170
	v_cvt_pk_bf16_f32 v126, v128, v196
	v_cvt_pk_bf16_f32 v127, v129, v200
	v_cvt_pk_bf16_f32 v128, v130, v204
	v_cvt_pk_bf16_f32 v129, v131, v220
	v_cvt_pk_bf16_f32 v130, v224, v0
	v_cvt_pk_bf16_f32 v131, v225, v142
	v_cvt_pk_bf16_f32 v132, v132, v168
	v_cvt_pk_bf16_f32 v133, v133, v194
	v_cvt_pk_bf16_f32 v134, v134, v198
	v_cvt_pk_bf16_f32 v135, v135, v202
	v_cvt_pk_bf16_f32 v136, v136, v206
	v_cvt_pk_bf16_f32 v137, v137, v222
	s_waitcnt lgkmcnt(5)
; #define LAS __attribute__((address_space(3)))
; #define MFMA32(a, b, c) __builtin_amdgcn_mfma_f32_32x32x16_bf16((a), (b), (c), 0, 0, 0)
; DI void diff_attn_phase(int wv, LAS unsigned char* lds, const bf16_t* qk, const bf16_t* vt, bf16_t* ob, const float* lq1, const float* lk1, const float* lq2, const float* lk2,
;                         const float* subg, int layer_idx) {
;     ...
;                 __builtin_amdgcn_sched_barrier(0);
; #pragma unroll
;                 for (int d = 0; d < 4; ++d) { O[d] = MFMA32(vf[d][0], p0, O[d]); O[d] = MFMA32(vf[d][1], p1, O[d]); }
;                 __builtin_amdgcn_sched_barrier(0);
; #pragma unroll
;                 for (int d = 0; d < 4; ++d)
; #pragma unroll
;                     for (int s2 = 0; s2 < 2; ++s2) vf[d][s2] = *(const LAS bf16x8*)(buf + voff + d * 32 * DA_VP + (32 + 16 * s2) * 2);
; #pragma unroll
;                 for (int d = 0; d < 4; ++d) { O[d] = MFMA32(vf[d][0], p2, O[d]); O[d] = MFMA32(vf[d][1], p3, O[d]); }
;             }
;             if (more) {
;                 LAS unsigned char* nb = lds + ((t + 1) & 1) * DA_BUF;
; #pragma unroll
;                 for (int i = 0; i < 2; ++i) { *(LAS u32x4*)(nb + kst_off + i * 32 * DA_KP) = gk[i]; *(LAS u32x4*)(nb + vst_off + i * 64 * DA_VP) = gv[i]; } }
;             __syncthreads();
	v_mfma_f32_32x32x16_bf16 v[34:49], v[86:89], v[122:125], v[34:49]
	s_waitcnt lgkmcnt(4)
	v_mfma_f32_32x32x16_bf16 v[34:49], v[82:85], v[126:129], v[34:49]
	v_add_f32_e64 v82, v138, v0
	v_add_f32_e64 v83, v139, v1
	s_waitcnt lgkmcnt(3)
	v_mfma_f32_32x32x16_bf16 v[18:33], v[78:81], v[122:125], v[18:33]
	v_add_f32_e64 v78, v82, v82
	v_add_f32_e64 v79, v82, v83
	v_mov_b32_e32 v143, v79
	v_add_f32_e64 v78, v140, v142
	v_add_f32_e64 v79, v141, v143
	v_pk_add_f32 v[78:79], v[78:79], v[78:79] op_sel_hi:[0,1]
	v_mov_b32_e32 v169, v79
	v_pk_add_f32 v[78:79], v[144:145], v[168:169]
	v_mfma_f32_32x32x16_bf16 v[50:65], v[94:97], v[122:125], v[50:65]
	v_pk_add_f32 v[78:79], v[78:79], v[78:79] op_sel_hi:[0,1]
	v_mov_b32_e32 v195, v79
	s_waitcnt lgkmcnt(1)
	v_mfma_f32_32x32x16_bf16 v[2:17], v[70:73], v[122:125], v[2:17]
	v_mfma_f32_32x32x16_bf16 v[18:33], v[74:77], v[126:129], v[18:33]
	v_add_f32_e64 v74, v170, v194
	v_add_f32_e64 v75, v171, v195
	v_pk_add_f32 v[74:75], v[74:75], v[74:75] op_sel_hi:[0,1]
	v_mov_b32_e32 v199, v75
	v_pk_add_f32 v[74:75], v[196:197], v[198:199]
	s_nop 0
	v_pk_add_f32 v[74:75], v[74:75], v[74:75] op_sel_hi:[0,1]
	v_mov_b32_e32 v203, v75
	v_mfma_f32_32x32x16_bf16 v[50:65], v[90:93], v[126:129], v[50:65]
	v_add_f32_e64 v70, v200, v202
	v_add_f32_e64 v71, v201, v203
	v_pk_add_f32 v[70:71], v[70:71], v[70:71] op_sel_hi:[0,1]
	v_mov_b32_e32 v207, v71
	v_pk_add_f32 v[70:71], v[204:205], v[206:207]
	s_nop 0
	v_pk_add_f32 v[70:71], v[70:71], v[70:71] op_sel_hi:[0,1]
	s_waitcnt lgkmcnt(0)
	v_mfma_f32_32x32x16_bf16 v[2:17], v[66:69], v[126:129], v[2:17]
	v_mov_b32_e32 v223, v71
	v_add_f32_e64 v70, v220, v222
	v_add_f32_e64 v71, v221, v223
	v_add_f32_e32 v159, v70, v71
	ds_read_b128 v[66:69], v191 offset:17472
	ds_read_b128 v[70:73], v191 offset:17504
	ds_read_b128 v[78:81], v191 offset:22080
	ds_read_b128 v[82:85], v191 offset:22112
	ds_read_b128 v[86:89], v191 offset:26688
	ds_read_b128 v[90:93], v191 offset:26720
	ds_read_b128 v[94:97], v191 offset:31296
	ds_read_b128 v[74:77], v191 offset:31328
	s_add_i32 s25, s25, 1
	s_bitcmp1_b32 s25, 0
	s_cselect_b32 s2, 0x8c00, 0
	s_add_i32 s2, s2, 0
	v_add_u32_e32 v0, s2, v167
	v_add_u32_e32 v223, s2, v208
	v_fmac_f32_e32 v159, v121, v118
	s_cmp_eq_u32 s1, s25
	s_mov_b32 s16, s14
	s_waitcnt vmcnt(3)
	ds_write_b128 v0, v[98:101]
	s_waitcnt vmcnt(1)
	ds_write_b128 v223, v[110:113] offset:17408
	ds_write_b128 v0, v[102:105] offset:8704
	s_waitcnt vmcnt(0)
	ds_write_b128 v223, v[106:109] offset:26624
	s_waitcnt lgkmcnt(11)
	v_mfma_f32_32x32x16_bf16 v[50:65], v[66:69], v[130:133], v[50:65]
	s_waitcnt lgkmcnt(10)
	v_mfma_f32_32x32x16_bf16 v[50:65], v[70:73], v[134:137], v[50:65]
	s_waitcnt lgkmcnt(9)
	v_mfma_f32_32x32x16_bf16 v[34:49], v[78:81], v[130:133], v[34:49]
	s_waitcnt lgkmcnt(8)
	v_mfma_f32_32x32x16_bf16 v[34:49], v[82:85], v[134:137], v[34:49]
	s_waitcnt lgkmcnt(7)
	v_mfma_f32_32x32x16_bf16 v[18:33], v[86:89], v[130:133], v[18:33]
	s_waitcnt lgkmcnt(6)
	v_mfma_f32_32x32x16_bf16 v[18:33], v[90:93], v[134:137], v[18:33]
	s_waitcnt lgkmcnt(5)
	v_mfma_f32_32x32x16_bf16 v[2:17], v[94:97], v[130:133], v[2:17]
	s_waitcnt lgkmcnt(0)
	s_barrier
	v_mfma_f32_32x32x16_bf16 v[2:17], v[74:77], v[134:137], v[2:17]
	s_cbranch_scc0 .LBB0_424
	s_branch .LBB0_427
